# v34: v33 + GLA S5 reads that do not depend on barrier B4 (V, decay scale) issued before it
# baseline (speedup 1.0000x reference)
; #define LAS __attribute__((address_space(3)))
; __device__ __forceinline__ void phase_gla(const Frame& F, int l, int gi, int ng, bool last, unsigned* cw) {
;     ...
;             __syncthreads();
; #pragma unroll
;             for (int ks = 0; ks < 4; ++ks) {
;                 const s16x8 a = *(const LAS s16x8*)(lds + GL_AM + ((it * 32 + r32) * 72 + ks * 16 + hh * 8) * 2);
;                 const s16x8 bb = *(const LAS s16x8*)(lds + GL_VT + ((et * 32 + r32) * 72 + ks * 16 + hh * 8) * 2);
;                 oacc = __builtin_amdgcn_mfma_f32_32x32x16_bf16(a, bb, oacc, 0, 0, 0); }
;             { const int cb = chunk_base(s), i0 = it * 32 + 4 * hh; const long rs = dir ? -(long)DM : (long)DM;
;               f16* ob = Oout + (size_t)(cb + (dir ? 63 - i0 : i0)) * DM + h * 256 + sl * 128 + et * 32 + r32;
; #pragma unroll
;               for (int e = 0; e < 16; ++e) ob[((e & 3) + 8 * (e >> 2)) * rs] = (f16)oacc[e]; }
; #pragma unroll
;             for (int q = 0; q < 2; ++q) {
; #pragma unroll
;                 for (int g4 = 0; g4 < 4; ++g4) { const f32x4 ev = *(const LAS f32x4*)(lds + GL_EB + (dt * 32 + g4 * 8 + hh * 4) * 4);
; #pragma unroll
;                     for (int e = 0; e < 4; ++e) Sacc[q][g4 * 4 + e] *= ev[e]; }
; #pragma unroll
;                 for (int ks = 0; ks < 4; ++ks) {
;                     const s16x8 a = *(const LAS s16x8*)(lds + GL_KT + ((dt * 32 + r32) * 72 + ks * 16 + hh * 8) * 2);
.LBB0_662:
	v_add_u32_e32 v176, s24, v121
	v_add_u32_e32 v177, s25, v121
	v_add_u32_e32 v178, s4, v121
	v_add_u32_e32 v179, s5, v121
	ds_read_b128 v[214:217], v171
	ds_read_b128 v[218:221], v171 offset:32
	ds_read_b128 v[222:225], v171 offset:64
	ds_read_b128 v[226:229], v171 offset:96
	ds_read_b128 v[230:233], v176
	ds_read_b128 v[242:245], v177
	ds_read_b128 v[246:249], v178
	ds_read_b128 v[62:65], v179
	s_waitcnt lgkmcnt(0)
	s_barrier
	ds_read_b128 v[184:187], v170
	ds_read_b128 v[188:191], v170 offset:32
	ds_read_b128 v[192:195], v170 offset:64
	ds_read_b128 v[200:203], v170 offset:96
	s_cmp_gt_u32 s14, 3
	s_waitcnt lgkmcnt(3)
	v_mfma_f32_32x32x16_bf16 v[34:49], v[184:187], v[214:217], v[34:49]
	ds_read_b128 v[50:53], v172
	s_waitcnt lgkmcnt(3)
	v_mfma_f32_32x32x16_bf16 v[34:49], v[188:191], v[218:221], v[34:49]
	ds_read_b128 v[54:57], v172 offset:32
	s_waitcnt lgkmcnt(3)
	v_mfma_f32_32x32x16_bf16 v[34:49], v[192:195], v[222:225], v[34:49]
	ds_read_b128 v[58:61], v172 offset:64
	s_waitcnt lgkmcnt(3)
	v_mfma_f32_32x32x16_bf16 v[34:49], v[200:203], v[226:229], v[34:49]
	ds_read_b128 v[180:183], v172 offset:96
	s_mov_b64 s[2:3], -1
	s_cbranch_scc0 .LBB0_664
	s_add_i32 s0, s37, 1
	s_and_b64 s[2:3], s[84:85], exec
	s_cselect_b32 s0, s7, s0
	s_lshl_b32 s0, s0, 6
	s_add_i32 s0, s0, s6
	s_mov_b64 s[2:3], 0
